# phase 16 load balance: the 32 Cmp2 GEMM tiles run on work-groups 128-159 (2 QG tiles) instead of 0-31 (3 QG tiles)
# speedup vs baseline: 1.0022x; 1.0022x over previous
.LBB0_418:
	s_and_b64 vcc, exec, s[0:1]
	s_cbranch_vccz .LBB0_461
	s_sub_i32 s81, s81, 0x80
	s_cmp_gt_u32 s81, 15
	s_mov_b64 s[0:1], -1
	s_cbranch_scc0 .LBB0_434
	s_cmp_lt_u32 s81, 32
	s_cbranch_scc1 .LBB0_422
	v_bfe_u32 v1, v170, 4, 2
	v_and_b32_e32 v158, 15, v170
	s_waitcnt lgkmcnt(0)
	v_lshlrev_b32_e32 v3, 2, v170
	v_lshlrev_b32_e32 v146, 4, v1
	v_lshlrev_b32_e32 v2, 6, v158
	v_and_b32_e32 v3, 32, v3
	v_bitop3_b32 v147, v146, v3, v2 bitop3:0x36
	s_mov_b64 s[0:1], 0

.LBB0_445:
	s_add_i32 s81, s81, 0x80
	s_movk_i32 s7, 0x400
	s_cmpk_gt_i32 s81, 0x27f
	v_readfirstlane_b32 s24, v170
	s_cbranch_scc1 .LBB0_461
	v_lshlrev_b32_e32 v2, 4, v170
	s_waitcnt lgkmcnt(0)
	v_add_u32_e32 v3, 0x2000, v2
	v_ashrrev_i32_e32 v4, 31, v3
	v_lshrrev_b32_e32 v4, 22, v4
	v_add_u32_e32 v4, v3, v4
	v_ashrrev_i32_e32 v10, 10, v4
	v_mul_i32_i24_e32 v4, 0x400, v10
	v_sub_u32_e32 v3, v3, v4
	v_lshrrev_b32_e32 v4, 4, v3
	v_bitop3_b32 v3, v4, v3, 32 bitop3:0x6c
	v_ashrrev_i32_e32 v4, 31, v3
	v_lshrrev_b32_e32 v4, 26, v4
	v_add_u32_e32 v4, v3, v4
	v_lshlrev_b32_e32 v5, 3, v10
	v_ashrrev_i32_e32 v11, 6, v4
	v_and_b32_e32 v5, -16, v5
	v_add_u32_e32 v5, v11, v5
	v_and_b32_e32 v6, 3, v11
	s_mov_b32 s0, 0x1fffe0
	v_lshrrev_b32_e32 v7, 2, v5
	v_lshlrev_b32_e32 v8, 1, v5
	v_and_or_b32 v6, v5, s0, v6
	v_and_b32_e32 v7, 4, v7
	v_and_b32_e32 v8, 24, v8
	v_and_b32_e32 v4, 0xc0, v4
	v_or3_b32 v6, v6, v7, v8
	v_sub_u32_e32 v3, v3, v4
	v_mov_b32_e32 v8, 1
	v_lshlrev_b32_e32 v7, 5, v10
	v_ashrrev_i16_sdwa v3, v8, sext(v3) dst_sel:DWORD dst_unused:UNUSED_PAD src0_sel:DWORD src1_sel:BYTE_0
	v_and_b32_e32 v7, 32, v7
	v_bfe_i32 v12, v3, 0, 16
	v_add_lshl_u32 v3, v7, v12, 1
	v_lshl_add_u32 v138, v6, 11, v3
	v_lshl_add_u32 v140, v5, 11, v3
	v_bfe_i32 v3, v170, 27, 1
	v_lshrrev_b32_e32 v3, 22, v3
	v_add_u32_e32 v3, v2, v3
	v_and_b32_e32 v3, 0xfffffc00, v3
	v_sub_u32_e32 v2, v2, v3
	v_lshrrev_b32_e32 v3, 4, v2
	v_ashrrev_i32_e32 v4, 31, v170
	v_bitop3_b32 v2, v3, v2, 32 bitop3:0x6c
	v_lshrrev_b32_e32 v4, 26, v4
	v_ashrrev_i32_e32 v3, 31, v2
	v_add_u32_e32 v4, v170, v4
	v_lshrrev_b32_e32 v3, 26, v3
	v_ashrrev_i32_e32 v14, 6, v4
	v_add_u32_e32 v3, v2, v3
	v_lshlrev_b32_e32 v4, 3, v14
	s_add_u32 s25, s66, 0x5800000
	v_ashrrev_i32_e32 v13, 6, v3
	v_and_b32_e32 v4, -16, v4
	s_addc_u32 s26, s67, 0
	v_add_u32_e32 v4, v13, v4
	v_and_b32_e32 v5, 3, v13
	s_ashr_i32 s28, s81, 31
	v_and_or_b32 v5, v4, s0, v5
	s_lshr_b32 s0, s28, 29
	s_add_i32 s0, s81, s0
	s_ashr_i32 s9, s24, 6
	s_ashr_i32 s1, s0, 3
	s_and_b32 s0, s0, -8
	s_ashr_i32 s8, s24, 8
	s_lshl_b32 s27, s9, 10
	s_sub_i32 s0, s81, s0
	s_cmp_lt_i32 s0, 0
	s_movk_i32 s2, 0x51
	s_cselect_b32 s2, s2, 0x50
	s_mul_i32 s0, s2, s0
	s_add_i32 s0, s0, s1
	s_mul_hi_i32 s1, s0, 0x66666667
	s_lshr_b32 s2, s1, 31
	s_ashr_i32 s1, s1, 4
	s_add_i32 s1, s1, s2
	s_lshl_b32 s2, s1, 3
	s_mul_i32 s1, s1, 40
	s_sub_i32 s0, s0, s1
	s_bfe_i32 s1, s0, 0x80000
	s_bfe_u32 s1, s1, 0x3000c
	s_add_i32 s1, s0, s1
	s_bfe_i32 s3, s1, 0x80000
	s_and_b32 s1, s1, 0xf8
	s_sub_i32 s0, s0, s1
	s_sext_i32_i16 s3, s3
	s_sext_i32_i8 s0, s0
	v_lshrrev_b32_e32 v6, 2, v4
	v_lshlrev_b32_e32 v7, 1, v4
	v_and_b32_e32 v3, 0xc0, v3
	s_lshr_b32 s6, s3, 3
	s_add_i32 s16, s2, s0
	v_and_b32_e32 v6, 4, v6
	v_and_b32_e32 v7, 24, v7
	v_sub_u32_e32 v2, v2, v3
	s_ashr_i32 s17, s16, 31
	s_bfe_i64 s[2:3], s[6:7], 0x100000
	v_or3_b32 v5, v5, v6, v7
	v_lshlrev_b32_e32 v6, 5, v14
	v_ashrrev_i16_sdwa v2, v8, sext(v2) dst_sel:DWORD dst_unused:UNUSED_PAD src0_sel:DWORD src1_sel:BYTE_0
	s_lshl_b64 s[0:1], s[16:17], 19
	s_lshl_b64 s[2:3], s[2:3], 19
	v_and_b32_e32 v6, 32, v6
	v_bfe_i32 v15, v2, 0, 16
	s_add_u32 s20, s25, s2
	v_add_lshl_u32 v2, v6, v15, 1
	s_addc_u32 s21, s26, s3
	s_add_i32 s29, s27, 0
	v_lshl_add_u32 v142, v5, 11, v2
	s_add_i32 m0, s29, 0x10000
	v_lshl_add_u32 v144, v4, 11, v2
	global_load_lds_dwordx4 v142, s[20:21]
	s_add_i32 m0, s29, 0x12000
	s_add_u32 s18, s64, s0
	global_load_lds_dwordx4 v138, s[20:21]
	s_addc_u32 s19, s65, s1
	s_mov_b32 m0, s29
	s_add_i32 s30, s29, 0x2000
	global_load_lds_dwordx4 v144, s[18:19]
	s_mov_b32 m0, s30
	s_add_u32 s0, s20, 0x40000
	global_load_lds_dwordx4 v140, s[18:19]
	s_addc_u32 s1, s21, 0
	s_add_i32 m0, s29, 0x14000
	v_mov_b32_e32 v143, v0
	global_load_lds_dwordx4 v142, s[0:1]
	s_add_i32 m0, s29, 0x16000
	v_mov_b32_e32 v139, v0
	global_load_lds_dwordx4 v138, s[0:1]
	s_add_u32 s0, s18, 0x40000
	s_addc_u32 s1, s19, 0
	s_add_i32 s31, s29, 0x4000
	s_mov_b32 m0, s31
	s_add_i32 s34, s29, 0x6000
	global_load_lds_dwordx4 v144, s[0:1]
	s_mov_b32 m0, s34
	v_mov_b32_e32 v145, v0
	global_load_lds_dwordx4 v140, s[0:1]
	v_mov_b32_e32 v141, v0
	v_lshl_add_u64 v[8:9], s[20:21], 0, v[142:143]
	v_lshl_add_u64 v[6:7], s[20:21], 0, v[138:139]
	v_lshl_add_u64 v[4:5], s[18:19], 0, v[144:145]
	s_cmp_lg_u32 s8, 1
	v_lshl_add_u64 v[2:3], s[18:19], 0, v[140:141]
	s_cbranch_scc1 .LBB0_448
	s_barrier
